# v27: v22 plus nt on the B-operand DMA loads of the in-projection GEMMs (layers 0,1), A/B experiment
# baseline (speedup 1.0000x reference)
.LBB0_278:
	ds_read_b128 v[130:133], v158
	ds_read_b128 v[134:137], v158 offset:1024
	ds_read_b128 v[162:165], v158 offset:2048
	ds_read_b128 v[166:169], v158 offset:3072
	s_add_u32 s0, s30, 0xfffc0080
	s_addc_u32 s1, s31, -1
	s_cmp_eq_u32 s60, 12
	s_cselect_b32 s37, s23, s1
	s_cselect_b32 s36, s56, s0
	s_cselect_b32 s35, s21, s59
	s_cselect_b32 s34, s57, s58
	v_lshl_add_u64 v[154:155], s[30:31], 0, v[148:149]
	s_add_i32 m0, s29, 0xc000
	ds_read_b128 v[170:173], v159
	ds_read_b128 v[174:177], v159 offset:1024
	ds_read_b128 v[178:181], v159 offset:2048
	ds_read_b128 v[182:185], v159 offset:3072
	ds_read_b128 v[186:189], v159 offset:4096
	ds_read_b128 v[190:193], v159 offset:5120
	ds_read_b128 v[194:197], v159 offset:6144
	ds_read_b128 v[198:201], v159 offset:7168
	global_load_lds_dwordx4 v[154:155], off
	v_lshl_add_u64 v[154:155], s[30:31], 0, v[146:147]
	s_add_i32 m0, s29, 0xe000
	s_nop 0
	global_load_lds_dwordx4 v[154:155], off
	s_waitcnt lgkmcnt(8)
	s_waitcnt vmcnt(10)
	s_barrier
	s_waitcnt lgkmcnt(0)
	s_waitcnt lgkmcnt(0)
	v_mfma_f32_16x16x32_bf16 v[126:129], v[130:133], v[170:173], v[126:129]
	v_mfma_f32_16x16x32_bf16 v[122:125], v[162:165], v[170:173], v[122:125]
	v_mfma_f32_16x16x32_bf16 v[118:121], v[130:133], v[178:181], v[118:121]
	v_mfma_f32_16x16x32_bf16 v[110:113], v[162:165], v[178:181], v[110:113]
	v_mfma_f32_16x16x32_bf16 v[102:105], v[130:133], v[186:189], v[102:105]
	v_mfma_f32_16x16x32_bf16 v[94:97], v[162:165], v[186:189], v[94:97]
	v_mfma_f32_16x16x32_bf16 v[86:89], v[130:133], v[194:197], v[86:89]
	v_mfma_f32_16x16x32_bf16 v[78:81], v[162:165], v[194:197], v[78:81]
	v_mfma_f32_16x16x32_bf16 v[126:129], v[134:137], v[174:177], v[126:129]
	v_mfma_f32_16x16x32_bf16 v[122:125], v[166:169], v[174:177], v[122:125]
	v_mfma_f32_16x16x32_bf16 v[118:121], v[134:137], v[182:185], v[118:121]
	v_mfma_f32_16x16x32_bf16 v[110:113], v[166:169], v[182:185], v[110:113]
	v_mfma_f32_16x16x32_bf16 v[102:105], v[134:137], v[190:193], v[102:105]
	v_mfma_f32_16x16x32_bf16 v[94:97], v[166:169], v[190:193], v[94:97]
	v_mfma_f32_16x16x32_bf16 v[86:89], v[134:137], v[198:201], v[86:89]
	v_mfma_f32_16x16x32_bf16 v[78:81], v[166:169], v[198:201], v[78:81]
	s_barrier
	s_add_i32 s0, s52, s41
	v_lshl_add_u64 v[154:155], s[34:35], 0, v[142:143]
	s_mov_b32 m0, s0
	ds_read_b128 v[202:205], v160
	ds_read_b128 v[206:209], v160 offset:1024
	ds_read_b128 v[210:213], v160 offset:2048
	ds_read_b128 v[214:217], v160 offset:3072
	global_load_lds_dwordx4 v[154:155], off nt
	v_lshl_add_u64 v[218:219], s[34:35], 0, v[138:139]
	s_add_i32 m0, s0, 0x2000
	s_nop 0
	global_load_lds_dwordx4 v[218:219], off nt
	s_waitcnt vmcnt(10)
	s_barrier
	s_waitcnt lgkmcnt(0)
	s_waitcnt lgkmcnt(0)
	v_mfma_f32_16x16x32_bf16 v[114:117], v[202:205], v[170:173], v[114:117]
	v_mfma_f32_16x16x32_bf16 v[106:109], v[210:213], v[170:173], v[106:109]
	v_mfma_f32_16x16x32_bf16 v[98:101], v[202:205], v[178:181], v[98:101]
	v_mfma_f32_16x16x32_bf16 v[90:93], v[210:213], v[178:181], v[90:93]
	v_mfma_f32_16x16x32_bf16 v[82:85], v[202:205], v[186:189], v[82:85]
	v_mfma_f32_16x16x32_bf16 v[74:77], v[210:213], v[186:189], v[74:77]
	v_mfma_f32_16x16x32_bf16 v[70:73], v[202:205], v[194:197], v[70:73]
	v_mfma_f32_16x16x32_bf16 v[66:69], v[210:213], v[194:197], v[66:69]
	v_mfma_f32_16x16x32_bf16 v[114:117], v[206:209], v[174:177], v[114:117]
	v_mfma_f32_16x16x32_bf16 v[106:109], v[214:217], v[174:177], v[106:109]
	v_mfma_f32_16x16x32_bf16 v[98:101], v[206:209], v[182:185], v[98:101]
	v_mfma_f32_16x16x32_bf16 v[90:93], v[214:217], v[182:185], v[90:93]
	v_mfma_f32_16x16x32_bf16 v[82:85], v[206:209], v[190:193], v[82:85]
	v_mfma_f32_16x16x32_bf16 v[74:77], v[214:217], v[190:193], v[74:77]
	v_mfma_f32_16x16x32_bf16 v[70:73], v[206:209], v[198:201], v[70:73]
	v_mfma_f32_16x16x32_bf16 v[66:69], v[214:217], v[198:201], v[66:69]
	s_mov_b32 m0, s29
	v_lshl_add_u64 v[220:221], s[36:37], 0, v[144:145]
	s_barrier
	ds_read_b128 v[170:173], v159 offset:16384
	ds_read_b128 v[174:177], v159 offset:17408
	ds_read_b128 v[178:181], v159 offset:18432
	ds_read_b128 v[182:185], v159 offset:19456
	ds_read_b128 v[186:189], v159 offset:20480
	ds_read_b128 v[190:193], v159 offset:21504
	ds_read_b128 v[194:197], v159 offset:22528
	ds_read_b128 v[198:201], v159 offset:23552
	global_load_lds_dwordx4 v[220:221], off
	v_lshl_add_u64 v[222:223], s[36:37], 0, v[140:141]
	s_mov_b32 m0, s43
	s_nop 0
	global_load_lds_dwordx4 v[222:223], off
	s_waitcnt vmcnt(10)
	s_barrier
	s_waitcnt lgkmcnt(0)
	s_waitcnt lgkmcnt(0)
	v_mfma_f32_16x16x32_bf16 v[62:65], v[130:133], v[170:173], v[62:65]
	v_mfma_f32_16x16x32_bf16 v[58:61], v[162:165], v[170:173], v[58:61]
	v_mfma_f32_16x16x32_bf16 v[54:57], v[130:133], v[178:181], v[54:57]
	v_mfma_f32_16x16x32_bf16 v[46:49], v[162:165], v[178:181], v[46:49]
	v_mfma_f32_16x16x32_bf16 v[38:41], v[130:133], v[186:189], v[38:41]
	v_mfma_f32_16x16x32_bf16 v[30:33], v[162:165], v[186:189], v[30:33]
	v_mfma_f32_16x16x32_bf16 v[22:25], v[130:133], v[194:197], v[22:25]
	v_mfma_f32_16x16x32_bf16 v[14:17], v[162:165], v[194:197], v[14:17]
	v_mfma_f32_16x16x32_bf16 v[62:65], v[134:137], v[174:177], v[62:65]
	v_mfma_f32_16x16x32_bf16 v[58:61], v[166:169], v[174:177], v[58:61]
	v_mfma_f32_16x16x32_bf16 v[54:57], v[134:137], v[182:185], v[54:57]
	v_mfma_f32_16x16x32_bf16 v[46:49], v[166:169], v[182:185], v[46:49]
	v_mfma_f32_16x16x32_bf16 v[38:41], v[134:137], v[190:193], v[38:41]
	v_mfma_f32_16x16x32_bf16 v[30:33], v[166:169], v[190:193], v[30:33]
	v_mfma_f32_16x16x32_bf16 v[22:25], v[134:137], v[198:201], v[22:25]
	v_mfma_f32_16x16x32_bf16 v[14:17], v[166:169], v[198:201], v[14:17]
	s_barrier
	s_add_u32 s0, s34, 0x40000
	s_addc_u32 s1, s35, 0
	s_add_i32 s61, s53, s41
	v_lshl_add_u64 v[130:131], s[0:1], 0, v[142:143]
	s_mov_b32 m0, s61
	s_nop 0
	global_load_lds_dwordx4 v[130:131], off nt
	v_lshl_add_u64 v[130:131], s[0:1], 0, v[138:139]
	s_add_i32 m0, s61, 0x2000
	s_nop 0
	global_load_lds_dwordx4 v[130:131], off nt
	s_waitcnt vmcnt(10)
	s_barrier
	v_mfma_f32_16x16x32_bf16 v[50:53], v[202:205], v[170:173], v[50:53]
	v_mfma_f32_16x16x32_bf16 v[42:45], v[210:213], v[170:173], v[42:45]
	v_mfma_f32_16x16x32_bf16 v[34:37], v[202:205], v[178:181], v[34:37]
	v_mfma_f32_16x16x32_bf16 v[26:29], v[210:213], v[178:181], v[26:29]
	v_mfma_f32_16x16x32_bf16 v[18:21], v[202:205], v[186:189], v[18:21]
	v_mfma_f32_16x16x32_bf16 v[10:13], v[210:213], v[186:189], v[10:13]
	v_mfma_f32_16x16x32_bf16 v[6:9], v[202:205], v[194:197], v[6:9]
	v_mfma_f32_16x16x32_bf16 v[2:5], v[210:213], v[194:197], v[2:5]
	v_mfma_f32_16x16x32_bf16 v[50:53], v[206:209], v[174:177], v[50:53]
	v_mfma_f32_16x16x32_bf16 v[42:45], v[214:217], v[174:177], v[42:45]
	v_mfma_f32_16x16x32_bf16 v[34:37], v[206:209], v[182:185], v[34:37]
	v_mfma_f32_16x16x32_bf16 v[26:29], v[214:217], v[182:185], v[26:29]
	v_mfma_f32_16x16x32_bf16 v[18:21], v[206:209], v[190:193], v[18:21]
	v_mfma_f32_16x16x32_bf16 v[10:13], v[214:217], v[190:193], v[10:13]
	v_mfma_f32_16x16x32_bf16 v[6:9], v[206:209], v[198:201], v[6:9]
	v_mfma_f32_16x16x32_bf16 v[2:5], v[214:217], v[198:201], v[2:5]
	s_add_i32 s61, 0, 0x18000
	v_add_u32_e32 v166, s61, v157
	s_barrier
	ds_read_b128 v[130:133], v166
	ds_read_b128 v[134:137], v166 offset:1024
	ds_read_b128 v[162:165], v166 offset:2048
	ds_read_b128 v[166:169], v166 offset:3072
	s_add_u32 s0, s36, 0x40000
	s_addc_u32 s1, s37, 0
	s_mov_b32 m0, s44
	v_lshl_add_u64 v[202:203], s[0:1], 0, v[144:145]
	ds_read_b128 v[170:173], v159 offset:32768
	ds_read_b128 v[174:177], v159 offset:33792
	ds_read_b128 v[178:181], v159 offset:34816
	ds_read_b128 v[182:185], v159 offset:35840
	ds_read_b128 v[186:189], v159 offset:36864
	ds_read_b128 v[190:193], v159 offset:37888
	ds_read_b128 v[194:197], v159 offset:38912
	ds_read_b128 v[198:201], v159 offset:39936
	global_load_lds_dwordx4 v[202:203], off
	v_lshl_add_u64 v[202:203], s[0:1], 0, v[140:141]
	s_mov_b32 m0, s45
	s_nop 0
	global_load_lds_dwordx4 v[202:203], off
	s_waitcnt lgkmcnt(8)
	s_waitcnt vmcnt(10)
	s_barrier
	s_waitcnt lgkmcnt(0)
	s_waitcnt lgkmcnt(0)
	v_mfma_f32_16x16x32_bf16 v[126:129], v[130:133], v[170:173], v[126:129]
	v_mfma_f32_16x16x32_bf16 v[122:125], v[162:165], v[170:173], v[122:125]
	v_mfma_f32_16x16x32_bf16 v[118:121], v[130:133], v[178:181], v[118:121]
	v_mfma_f32_16x16x32_bf16 v[110:113], v[162:165], v[178:181], v[110:113]
	v_mfma_f32_16x16x32_bf16 v[102:105], v[130:133], v[186:189], v[102:105]
	v_mfma_f32_16x16x32_bf16 v[94:97], v[162:165], v[186:189], v[94:97]
	v_mfma_f32_16x16x32_bf16 v[86:89], v[130:133], v[194:197], v[86:89]
	v_mfma_f32_16x16x32_bf16 v[78:81], v[162:165], v[194:197], v[78:81]
	v_mfma_f32_16x16x32_bf16 v[126:129], v[134:137], v[174:177], v[126:129]
	v_mfma_f32_16x16x32_bf16 v[122:125], v[166:169], v[174:177], v[122:125]
	v_mfma_f32_16x16x32_bf16 v[118:121], v[134:137], v[182:185], v[118:121]
	v_mfma_f32_16x16x32_bf16 v[110:113], v[166:169], v[182:185], v[110:113]
	v_mfma_f32_16x16x32_bf16 v[102:105], v[134:137], v[190:193], v[102:105]
	v_mfma_f32_16x16x32_bf16 v[94:97], v[166:169], v[190:193], v[94:97]
	v_mfma_f32_16x16x32_bf16 v[86:89], v[134:137], v[198:201], v[86:89]
	v_mfma_f32_16x16x32_bf16 v[78:81], v[166:169], v[198:201], v[78:81]
	s_barrier
	s_add_i32 s36, 0, 0x1c000
	s_add_i32 s0, s61, s41
	v_add_u32_e32 v214, s36, v157
	v_lshl_add_u64 v[154:155], v[154:155], 0, s[16:17]
	s_mov_b32 m0, s0
	ds_read_b128 v[202:205], v214
	ds_read_b128 v[206:209], v214 offset:1024
	ds_read_b128 v[210:213], v214 offset:2048
	ds_read_b128 v[214:217], v214 offset:3072
	global_load_lds_dwordx4 v[154:155], off nt
	v_lshl_add_u64 v[154:155], v[218:219], 0, s[16:17]
	s_add_i32 m0, s0, 0x2000
	s_nop 0
	global_load_lds_dwordx4 v[154:155], off nt
	s_waitcnt vmcnt(10)
	s_barrier
	s_waitcnt lgkmcnt(0)
	s_waitcnt lgkmcnt(0)
	v_mfma_f32_16x16x32_bf16 v[114:117], v[202:205], v[170:173], v[114:117]
	v_mfma_f32_16x16x32_bf16 v[106:109], v[210:213], v[170:173], v[106:109]
	v_mfma_f32_16x16x32_bf16 v[98:101], v[202:205], v[178:181], v[98:101]
	v_mfma_f32_16x16x32_bf16 v[90:93], v[210:213], v[178:181], v[90:93]
	v_mfma_f32_16x16x32_bf16 v[82:85], v[202:205], v[186:189], v[82:85]
	v_mfma_f32_16x16x32_bf16 v[74:77], v[210:213], v[186:189], v[74:77]
	v_mfma_f32_16x16x32_bf16 v[70:73], v[202:205], v[194:197], v[70:73]
	v_mfma_f32_16x16x32_bf16 v[66:69], v[210:213], v[194:197], v[66:69]
	v_mfma_f32_16x16x32_bf16 v[114:117], v[206:209], v[174:177], v[114:117]
	v_mfma_f32_16x16x32_bf16 v[106:109], v[214:217], v[174:177], v[106:109]
	v_mfma_f32_16x16x32_bf16 v[98:101], v[206:209], v[182:185], v[98:101]
	v_mfma_f32_16x16x32_bf16 v[90:93], v[214:217], v[182:185], v[90:93]
	v_mfma_f32_16x16x32_bf16 v[82:85], v[206:209], v[190:193], v[82:85]
	v_mfma_f32_16x16x32_bf16 v[74:77], v[214:217], v[190:193], v[74:77]
	v_mfma_f32_16x16x32_bf16 v[70:73], v[206:209], v[198:201], v[70:73]
	v_mfma_f32_16x16x32_bf16 v[66:69], v[214:217], v[198:201], v[66:69]
	s_mov_b32 m0, s49
	v_lshl_add_u64 v[154:155], v[220:221], 0, s[16:17]
	s_barrier
	ds_read_b128 v[170:173], v159 offset:49152
	ds_read_b128 v[174:177], v159 offset:50176
	ds_read_b128 v[178:181], v159 offset:51200
	ds_read_b128 v[182:185], v159 offset:52224
	ds_read_b128 v[186:189], v159 offset:53248
	ds_read_b128 v[190:193], v159 offset:54272
	ds_read_b128 v[194:197], v159 offset:55296
	ds_read_b128 v[198:201], v159 offset:56320
	global_load_lds_dwordx4 v[154:155], off
	v_lshl_add_u64 v[154:155], v[222:223], 0, s[16:17]
	s_mov_b32 m0, s51
	s_nop 0
	global_load_lds_dwordx4 v[154:155], off
	s_waitcnt vmcnt(10)
	s_barrier
	s_waitcnt lgkmcnt(0)
	s_waitcnt lgkmcnt(0)
	v_mfma_f32_16x16x32_bf16 v[62:65], v[130:133], v[170:173], v[62:65]
	v_mfma_f32_16x16x32_bf16 v[58:61], v[162:165], v[170:173], v[58:61]
	v_mfma_f32_16x16x32_bf16 v[54:57], v[130:133], v[178:181], v[54:57]
	v_mfma_f32_16x16x32_bf16 v[46:49], v[162:165], v[178:181], v[46:49]
	v_mfma_f32_16x16x32_bf16 v[38:41], v[130:133], v[186:189], v[38:41]
	v_mfma_f32_16x16x32_bf16 v[30:33], v[162:165], v[186:189], v[30:33]
	v_mfma_f32_16x16x32_bf16 v[22:25], v[130:133], v[194:197], v[22:25]
	v_mfma_f32_16x16x32_bf16 v[14:17], v[162:165], v[194:197], v[14:17]
	v_mfma_f32_16x16x32_bf16 v[62:65], v[134:137], v[174:177], v[62:65]
	v_mfma_f32_16x16x32_bf16 v[58:61], v[166:169], v[174:177], v[58:61]
	v_mfma_f32_16x16x32_bf16 v[54:57], v[134:137], v[182:185], v[54:57]
	v_mfma_f32_16x16x32_bf16 v[46:49], v[166:169], v[182:185], v[46:49]
	v_mfma_f32_16x16x32_bf16 v[38:41], v[134:137], v[190:193], v[38:41]
	v_mfma_f32_16x16x32_bf16 v[30:33], v[166:169], v[190:193], v[30:33]
	v_mfma_f32_16x16x32_bf16 v[22:25], v[134:137], v[198:201], v[22:25]
	v_mfma_f32_16x16x32_bf16 v[14:17], v[166:169], v[198:201], v[14:17]
	s_barrier
	s_add_u32 s0, s34, 0x40080
	s_addc_u32 s1, s35, 0
	s_add_i32 s34, s36, s41
	v_lshl_add_u64 v[130:131], s[0:1], 0, v[142:143]
	s_mov_b32 m0, s34
	s_nop 0
	global_load_lds_dwordx4 v[130:131], off nt
	v_lshl_add_u64 v[130:131], s[0:1], 0, v[138:139]
	s_add_i32 m0, s34, 0x2000
	s_nop 0
	global_load_lds_dwordx4 v[130:131], off nt
	s_waitcnt vmcnt(10)
	s_barrier
	v_mfma_f32_16x16x32_bf16 v[50:53], v[202:205], v[170:173], v[50:53]
	v_mfma_f32_16x16x32_bf16 v[42:45], v[210:213], v[170:173], v[42:45]
	v_mfma_f32_16x16x32_bf16 v[34:37], v[202:205], v[178:181], v[34:37]
	v_mfma_f32_16x16x32_bf16 v[26:29], v[210:213], v[178:181], v[26:29]
	v_mfma_f32_16x16x32_bf16 v[18:21], v[202:205], v[186:189], v[18:21]
	v_mfma_f32_16x16x32_bf16 v[10:13], v[210:213], v[186:189], v[10:13]
	v_mfma_f32_16x16x32_bf16 v[6:9], v[202:205], v[194:197], v[6:9]
	v_mfma_f32_16x16x32_bf16 v[2:5], v[210:213], v[194:197], v[2:5]
	v_mfma_f32_16x16x32_bf16 v[50:53], v[206:209], v[174:177], v[50:53]
	v_mfma_f32_16x16x32_bf16 v[42:45], v[214:217], v[174:177], v[42:45]
	v_mfma_f32_16x16x32_bf16 v[34:37], v[206:209], v[182:185], v[34:37]
	v_mfma_f32_16x16x32_bf16 v[26:29], v[214:217], v[182:185], v[26:29]
	v_mfma_f32_16x16x32_bf16 v[18:21], v[206:209], v[190:193], v[18:21]
	v_mfma_f32_16x16x32_bf16 v[10:13], v[214:217], v[190:193], v[10:13]
	v_mfma_f32_16x16x32_bf16 v[6:9], v[206:209], v[198:201], v[6:9]
	v_mfma_f32_16x16x32_bf16 v[2:5], v[214:217], v[198:201], v[2:5]
	s_add_i32 s60, s60, 2
	s_add_u32 s58, s58, 0x100
	s_addc_u32 s59, s59, 0
	s_add_u32 s30, s30, 0x100
	s_addc_u32 s31, s31, 0
	s_cmp_gt_u32 s60, 13
	s_barrier
	s_cbranch_scc0 .LBB0_278
	v_mov_b32_e32 v162, v1
	v_mov_b32_e32 v163, v156
	s_cmp_gt_i32 s55, 11
	s_mov_b64 s[30:31], -1
	s_cbranch_scc0 .LBB0_286
	s_cmp_eq_u32 s55, 12
	s_cselect_b64 s[0:1], -1, 0
	s_and_b64 s[0:1], s[0:1], s[18:19]
	v_cmp_gt_i32_e32 vcc, 2, v163
	s_and_b64 s[0:1], s[0:1], vcc
	s_and_saveexec_b64 s[30:31], s[0:1]
	s_cbranch_execz .LBB0_285
	v_lshlrev_b32_e32 v154, 3, v163
	s_andn2_b64 vcc, exec, s[12:13]
	v_ashrrev_i32_e32 v155, 31, v154
	s_cbranch_vccnz .LBB0_283
	v_lshl_add_u64 v[134:135], v[154:155], 2, s[8:9]
	global_load_dwordx4 v[130:133], v[134:135], off
	s_nop 0
	global_load_dwordx4 v[134:137], v[134:135], off offset:16
	s_branch .LBB0_284

.LBB0_895:
	ds_read_b128 v[156:159], v152
	ds_read_b128 v[160:163], v152 offset:1024
	ds_read_b128 v[164:167], v152 offset:2048
	ds_read_b128 v[168:171], v152 offset:3072
	s_add_u32 s0, s30, 0xfffc0080
	s_addc_u32 s1, s31, -1
	s_cmp_eq_u32 s55, 12
	s_cselect_b32 s37, s23, s1
	s_cselect_b32 s36, s51, s0
	s_cselect_b32 s35, s21, s54
	s_cselect_b32 s34, s52, s53
	v_lshl_add_u64 v[148:149], s[30:31], 0, v[140:141]
	s_add_i32 m0, s25, 0xc000
	ds_read_b128 v[172:175], v153
	ds_read_b128 v[176:179], v153 offset:1024
	ds_read_b128 v[180:183], v153 offset:2048
	ds_read_b128 v[184:187], v153 offset:3072
	ds_read_b128 v[188:191], v153 offset:4096
	ds_read_b128 v[192:195], v153 offset:5120
	ds_read_b128 v[196:199], v153 offset:6144
	ds_read_b128 v[200:203], v153 offset:7168
	global_load_lds_dwordx4 v[148:149], off
	v_lshl_add_u64 v[148:149], s[30:31], 0, v[138:139]
	s_add_i32 m0, s25, 0xe000
	s_nop 0
	global_load_lds_dwordx4 v[148:149], off
	s_waitcnt lgkmcnt(8)
	s_waitcnt vmcnt(10)
	s_barrier
	s_waitcnt lgkmcnt(0)
	s_waitcnt lgkmcnt(0)
	v_mfma_f32_16x16x32_bf16 v[126:129], v[156:159], v[172:175], v[126:129]
	v_mfma_f32_16x16x32_bf16 v[122:125], v[164:167], v[172:175], v[122:125]
	v_mfma_f32_16x16x32_bf16 v[118:121], v[156:159], v[180:183], v[118:121]
	v_mfma_f32_16x16x32_bf16 v[110:113], v[164:167], v[180:183], v[110:113]
	v_mfma_f32_16x16x32_bf16 v[102:105], v[156:159], v[188:191], v[102:105]
	v_mfma_f32_16x16x32_bf16 v[94:97], v[164:167], v[188:191], v[94:97]
	v_mfma_f32_16x16x32_bf16 v[86:89], v[156:159], v[196:199], v[86:89]
	v_mfma_f32_16x16x32_bf16 v[78:81], v[164:167], v[196:199], v[78:81]
	v_mfma_f32_16x16x32_bf16 v[126:129], v[160:163], v[176:179], v[126:129]
	v_mfma_f32_16x16x32_bf16 v[122:125], v[168:171], v[176:179], v[122:125]
	v_mfma_f32_16x16x32_bf16 v[118:121], v[160:163], v[184:187], v[118:121]
	v_mfma_f32_16x16x32_bf16 v[110:113], v[168:171], v[184:187], v[110:113]
	v_mfma_f32_16x16x32_bf16 v[102:105], v[160:163], v[192:195], v[102:105]
	v_mfma_f32_16x16x32_bf16 v[94:97], v[168:171], v[192:195], v[94:97]
	v_mfma_f32_16x16x32_bf16 v[86:89], v[160:163], v[200:203], v[86:89]
	v_mfma_f32_16x16x32_bf16 v[78:81], v[168:171], v[200:203], v[78:81]
	s_barrier
	s_add_i32 s0, s47, s11
	v_lshl_add_u64 v[148:149], s[34:35], 0, v[134:135]
	s_mov_b32 m0, s0
	ds_read_b128 v[204:207], v154
	ds_read_b128 v[208:211], v154 offset:1024
	ds_read_b128 v[212:215], v154 offset:2048
	ds_read_b128 v[216:219], v154 offset:3072
	global_load_lds_dwordx4 v[148:149], off nt
	v_lshl_add_u64 v[220:221], s[34:35], 0, v[130:131]
	s_add_i32 m0, s0, 0x2000
	s_nop 0
	global_load_lds_dwordx4 v[220:221], off nt
	s_waitcnt vmcnt(10)
	s_barrier
	s_waitcnt lgkmcnt(0)
	s_waitcnt lgkmcnt(0)
	v_mfma_f32_16x16x32_bf16 v[114:117], v[204:207], v[172:175], v[114:117]
	v_mfma_f32_16x16x32_bf16 v[106:109], v[212:215], v[172:175], v[106:109]
	v_mfma_f32_16x16x32_bf16 v[98:101], v[204:207], v[180:183], v[98:101]
	v_mfma_f32_16x16x32_bf16 v[90:93], v[212:215], v[180:183], v[90:93]
	v_mfma_f32_16x16x32_bf16 v[82:85], v[204:207], v[188:191], v[82:85]
	v_mfma_f32_16x16x32_bf16 v[74:77], v[212:215], v[188:191], v[74:77]
	v_mfma_f32_16x16x32_bf16 v[70:73], v[204:207], v[196:199], v[70:73]
	v_mfma_f32_16x16x32_bf16 v[66:69], v[212:215], v[196:199], v[66:69]
	v_mfma_f32_16x16x32_bf16 v[114:117], v[208:211], v[176:179], v[114:117]
	v_mfma_f32_16x16x32_bf16 v[106:109], v[216:219], v[176:179], v[106:109]
	v_mfma_f32_16x16x32_bf16 v[98:101], v[208:211], v[184:187], v[98:101]
	v_mfma_f32_16x16x32_bf16 v[90:93], v[216:219], v[184:187], v[90:93]
	v_mfma_f32_16x16x32_bf16 v[82:85], v[208:211], v[192:195], v[82:85]
	v_mfma_f32_16x16x32_bf16 v[74:77], v[216:219], v[192:195], v[74:77]
	v_mfma_f32_16x16x32_bf16 v[70:73], v[208:211], v[200:203], v[70:73]
	v_mfma_f32_16x16x32_bf16 v[66:69], v[216:219], v[200:203], v[66:69]
	s_mov_b32 m0, s25
	v_lshl_add_u64 v[222:223], s[36:37], 0, v[136:137]
	s_barrier
	ds_read_b128 v[172:175], v153 offset:16384
	ds_read_b128 v[176:179], v153 offset:17408
	ds_read_b128 v[180:183], v153 offset:18432
	ds_read_b128 v[184:187], v153 offset:19456
	ds_read_b128 v[188:191], v153 offset:20480
	ds_read_b128 v[192:195], v153 offset:21504
	ds_read_b128 v[196:199], v153 offset:22528
	ds_read_b128 v[200:203], v153 offset:23552
	global_load_lds_dwordx4 v[222:223], off
	v_lshl_add_u64 v[224:225], s[36:37], 0, v[132:133]
	s_mov_b32 m0, s39
	s_nop 0
	global_load_lds_dwordx4 v[224:225], off
	s_waitcnt vmcnt(10)
	s_barrier
	s_waitcnt lgkmcnt(0)
	s_waitcnt lgkmcnt(0)
	v_mfma_f32_16x16x32_bf16 v[62:65], v[156:159], v[172:175], v[62:65]
	v_mfma_f32_16x16x32_bf16 v[58:61], v[164:167], v[172:175], v[58:61]
	v_mfma_f32_16x16x32_bf16 v[54:57], v[156:159], v[180:183], v[54:57]
	v_mfma_f32_16x16x32_bf16 v[46:49], v[164:167], v[180:183], v[46:49]
	v_mfma_f32_16x16x32_bf16 v[38:41], v[156:159], v[188:191], v[38:41]
	v_mfma_f32_16x16x32_bf16 v[30:33], v[164:167], v[188:191], v[30:33]
	v_mfma_f32_16x16x32_bf16 v[22:25], v[156:159], v[196:199], v[22:25]
	v_mfma_f32_16x16x32_bf16 v[14:17], v[164:167], v[196:199], v[14:17]
	v_mfma_f32_16x16x32_bf16 v[62:65], v[160:163], v[176:179], v[62:65]
	v_mfma_f32_16x16x32_bf16 v[58:61], v[168:171], v[176:179], v[58:61]
	v_mfma_f32_16x16x32_bf16 v[54:57], v[160:163], v[184:187], v[54:57]
	v_mfma_f32_16x16x32_bf16 v[46:49], v[168:171], v[184:187], v[46:49]
	v_mfma_f32_16x16x32_bf16 v[38:41], v[160:163], v[192:195], v[38:41]
	v_mfma_f32_16x16x32_bf16 v[30:33], v[168:171], v[192:195], v[30:33]
	v_mfma_f32_16x16x32_bf16 v[22:25], v[160:163], v[200:203], v[22:25]
	v_mfma_f32_16x16x32_bf16 v[14:17], v[168:171], v[200:203], v[14:17]
	s_barrier
	s_add_u32 s0, s34, 0x40000
	s_addc_u32 s1, s35, 0
	s_add_i32 s56, s48, s11
	v_lshl_add_u64 v[156:157], s[0:1], 0, v[134:135]
	s_mov_b32 m0, s56
	s_nop 0
	global_load_lds_dwordx4 v[156:157], off nt
	v_lshl_add_u64 v[156:157], s[0:1], 0, v[130:131]
	s_add_i32 m0, s56, 0x2000
	s_nop 0
	global_load_lds_dwordx4 v[156:157], off nt
	s_waitcnt vmcnt(10)
	s_barrier
	v_mfma_f32_16x16x32_bf16 v[50:53], v[204:207], v[172:175], v[50:53]
	v_mfma_f32_16x16x32_bf16 v[42:45], v[212:215], v[172:175], v[42:45]
	v_mfma_f32_16x16x32_bf16 v[34:37], v[204:207], v[180:183], v[34:37]
	v_mfma_f32_16x16x32_bf16 v[26:29], v[212:215], v[180:183], v[26:29]
	v_mfma_f32_16x16x32_bf16 v[18:21], v[204:207], v[188:191], v[18:21]
	v_mfma_f32_16x16x32_bf16 v[10:13], v[212:215], v[188:191], v[10:13]
	v_mfma_f32_16x16x32_bf16 v[6:9], v[204:207], v[196:199], v[6:9]
	v_mfma_f32_16x16x32_bf16 v[2:5], v[212:215], v[196:199], v[2:5]
	v_mfma_f32_16x16x32_bf16 v[50:53], v[208:211], v[176:179], v[50:53]
	v_mfma_f32_16x16x32_bf16 v[42:45], v[216:219], v[176:179], v[42:45]
	v_mfma_f32_16x16x32_bf16 v[34:37], v[208:211], v[184:187], v[34:37]
	v_mfma_f32_16x16x32_bf16 v[26:29], v[216:219], v[184:187], v[26:29]
	v_mfma_f32_16x16x32_bf16 v[18:21], v[208:211], v[192:195], v[18:21]
	v_mfma_f32_16x16x32_bf16 v[10:13], v[216:219], v[192:195], v[10:13]
	v_mfma_f32_16x16x32_bf16 v[6:9], v[208:211], v[200:203], v[6:9]
	v_mfma_f32_16x16x32_bf16 v[2:5], v[216:219], v[200:203], v[2:5]
	s_add_i32 s56, 0, 0x18000
	v_add_u32_e32 v146, s56, v151
	s_barrier
	ds_read_b128 v[156:159], v146
	ds_read_b128 v[160:163], v146 offset:1024
	ds_read_b128 v[164:167], v146 offset:2048
	ds_read_b128 v[168:171], v146 offset:3072
	s_add_u32 s0, s36, 0x40000
	s_addc_u32 s1, s37, 0
	s_mov_b32 m0, s40
	v_lshl_add_u64 v[204:205], s[0:1], 0, v[136:137]
	ds_read_b128 v[172:175], v153 offset:32768
	ds_read_b128 v[176:179], v153 offset:33792
	ds_read_b128 v[180:183], v153 offset:34816
	ds_read_b128 v[184:187], v153 offset:35840
	ds_read_b128 v[188:191], v153 offset:36864
	ds_read_b128 v[192:195], v153 offset:37888
	ds_read_b128 v[196:199], v153 offset:38912
	ds_read_b128 v[200:203], v153 offset:39936
	global_load_lds_dwordx4 v[204:205], off
	v_lshl_add_u64 v[204:205], s[0:1], 0, v[132:133]
	s_mov_b32 m0, s41
	s_nop 0
	global_load_lds_dwordx4 v[204:205], off
	s_waitcnt lgkmcnt(8)
	s_waitcnt vmcnt(10)
	s_barrier
	s_waitcnt lgkmcnt(0)
	s_waitcnt lgkmcnt(0)
	v_mfma_f32_16x16x32_bf16 v[126:129], v[156:159], v[172:175], v[126:129]
	v_mfma_f32_16x16x32_bf16 v[122:125], v[164:167], v[172:175], v[122:125]
	v_mfma_f32_16x16x32_bf16 v[118:121], v[156:159], v[180:183], v[118:121]
	v_mfma_f32_16x16x32_bf16 v[110:113], v[164:167], v[180:183], v[110:113]
	v_mfma_f32_16x16x32_bf16 v[102:105], v[156:159], v[188:191], v[102:105]
	v_mfma_f32_16x16x32_bf16 v[94:97], v[164:167], v[188:191], v[94:97]
	v_mfma_f32_16x16x32_bf16 v[86:89], v[156:159], v[196:199], v[86:89]
	v_mfma_f32_16x16x32_bf16 v[78:81], v[164:167], v[196:199], v[78:81]
	v_mfma_f32_16x16x32_bf16 v[126:129], v[160:163], v[176:179], v[126:129]
	v_mfma_f32_16x16x32_bf16 v[122:125], v[168:171], v[176:179], v[122:125]
	v_mfma_f32_16x16x32_bf16 v[118:121], v[160:163], v[184:187], v[118:121]
	v_mfma_f32_16x16x32_bf16 v[110:113], v[168:171], v[184:187], v[110:113]
	v_mfma_f32_16x16x32_bf16 v[102:105], v[160:163], v[192:195], v[102:105]
	v_mfma_f32_16x16x32_bf16 v[94:97], v[168:171], v[192:195], v[94:97]
	v_mfma_f32_16x16x32_bf16 v[86:89], v[160:163], v[200:203], v[86:89]
	v_mfma_f32_16x16x32_bf16 v[78:81], v[168:171], v[200:203], v[78:81]
	s_barrier
	s_add_i32 s36, 0, 0x1c000
	s_add_i32 s0, s56, s11
	v_add_u32_e32 v146, s36, v151
	v_lshl_add_u64 v[148:149], v[148:149], 0, s[16:17]
	s_mov_b32 m0, s0
	ds_read_b128 v[204:207], v146
	ds_read_b128 v[208:211], v146 offset:1024
	ds_read_b128 v[212:215], v146 offset:2048
	ds_read_b128 v[216:219], v146 offset:3072
	global_load_lds_dwordx4 v[148:149], off nt
	v_lshl_add_u64 v[148:149], v[220:221], 0, s[16:17]
	s_add_i32 m0, s0, 0x2000
	s_nop 0
	global_load_lds_dwordx4 v[148:149], off nt
	s_waitcnt vmcnt(10)
	s_barrier
	s_waitcnt lgkmcnt(0)
	s_waitcnt lgkmcnt(0)
	v_mfma_f32_16x16x32_bf16 v[114:117], v[204:207], v[172:175], v[114:117]
	v_mfma_f32_16x16x32_bf16 v[106:109], v[212:215], v[172:175], v[106:109]
	v_mfma_f32_16x16x32_bf16 v[98:101], v[204:207], v[180:183], v[98:101]
	v_mfma_f32_16x16x32_bf16 v[90:93], v[212:215], v[180:183], v[90:93]
	v_mfma_f32_16x16x32_bf16 v[82:85], v[204:207], v[188:191], v[82:85]
	v_mfma_f32_16x16x32_bf16 v[74:77], v[212:215], v[188:191], v[74:77]
	v_mfma_f32_16x16x32_bf16 v[70:73], v[204:207], v[196:199], v[70:73]
	v_mfma_f32_16x16x32_bf16 v[66:69], v[212:215], v[196:199], v[66:69]
	v_mfma_f32_16x16x32_bf16 v[114:117], v[208:211], v[176:179], v[114:117]
	v_mfma_f32_16x16x32_bf16 v[106:109], v[216:219], v[176:179], v[106:109]
	v_mfma_f32_16x16x32_bf16 v[98:101], v[208:211], v[184:187], v[98:101]
	v_mfma_f32_16x16x32_bf16 v[90:93], v[216:219], v[184:187], v[90:93]
	v_mfma_f32_16x16x32_bf16 v[82:85], v[208:211], v[192:195], v[82:85]
	v_mfma_f32_16x16x32_bf16 v[74:77], v[216:219], v[192:195], v[74:77]
	v_mfma_f32_16x16x32_bf16 v[70:73], v[208:211], v[200:203], v[70:73]
	v_mfma_f32_16x16x32_bf16 v[66:69], v[216:219], v[200:203], v[66:69]
	s_mov_b32 m0, s45
	v_lshl_add_u64 v[148:149], v[222:223], 0, s[16:17]
	s_barrier
	ds_read_b128 v[172:175], v153 offset:49152
	ds_read_b128 v[176:179], v153 offset:50176
	ds_read_b128 v[180:183], v153 offset:51200
	ds_read_b128 v[184:187], v153 offset:52224
	ds_read_b128 v[188:191], v153 offset:53248
	ds_read_b128 v[192:195], v153 offset:54272
	ds_read_b128 v[196:199], v153 offset:55296
	ds_read_b128 v[200:203], v153 offset:56320
	global_load_lds_dwordx4 v[148:149], off
	v_lshl_add_u64 v[148:149], v[224:225], 0, s[16:17]
	s_mov_b32 m0, s46
	s_nop 0
	global_load_lds_dwordx4 v[148:149], off
	s_waitcnt vmcnt(10)
	s_barrier
	s_waitcnt lgkmcnt(0)
	s_waitcnt lgkmcnt(0)
	v_mfma_f32_16x16x32_bf16 v[62:65], v[156:159], v[172:175], v[62:65]
	v_mfma_f32_16x16x32_bf16 v[58:61], v[164:167], v[172:175], v[58:61]
	v_mfma_f32_16x16x32_bf16 v[54:57], v[156:159], v[180:183], v[54:57]
	v_mfma_f32_16x16x32_bf16 v[46:49], v[164:167], v[180:183], v[46:49]
	v_mfma_f32_16x16x32_bf16 v[38:41], v[156:159], v[188:191], v[38:41]
	v_mfma_f32_16x16x32_bf16 v[30:33], v[164:167], v[188:191], v[30:33]
	v_mfma_f32_16x16x32_bf16 v[22:25], v[156:159], v[196:199], v[22:25]
	v_mfma_f32_16x16x32_bf16 v[14:17], v[164:167], v[196:199], v[14:17]
	v_mfma_f32_16x16x32_bf16 v[62:65], v[160:163], v[176:179], v[62:65]
	v_mfma_f32_16x16x32_bf16 v[58:61], v[168:171], v[176:179], v[58:61]
	v_mfma_f32_16x16x32_bf16 v[54:57], v[160:163], v[184:187], v[54:57]
	v_mfma_f32_16x16x32_bf16 v[46:49], v[168:171], v[184:187], v[46:49]
	v_mfma_f32_16x16x32_bf16 v[38:41], v[160:163], v[192:195], v[38:41]
	v_mfma_f32_16x16x32_bf16 v[30:33], v[168:171], v[192:195], v[30:33]
	v_mfma_f32_16x16x32_bf16 v[22:25], v[160:163], v[200:203], v[22:25]
	v_mfma_f32_16x16x32_bf16 v[14:17], v[168:171], v[200:203], v[14:17]
	s_barrier
	s_add_u32 s0, s34, 0x40080
	s_addc_u32 s1, s35, 0
	s_add_i32 s34, s36, s11
	v_lshl_add_u64 v[148:149], s[0:1], 0, v[134:135]
	s_mov_b32 m0, s34
	s_nop 0
	global_load_lds_dwordx4 v[148:149], off nt
	v_lshl_add_u64 v[148:149], s[0:1], 0, v[130:131]
	s_add_i32 m0, s34, 0x2000
	s_nop 0
	global_load_lds_dwordx4 v[148:149], off nt
	s_waitcnt vmcnt(10)
	s_barrier
	v_mfma_f32_16x16x32_bf16 v[50:53], v[204:207], v[172:175], v[50:53]
	v_mfma_f32_16x16x32_bf16 v[42:45], v[212:215], v[172:175], v[42:45]
	v_mfma_f32_16x16x32_bf16 v[34:37], v[204:207], v[180:183], v[34:37]
	v_mfma_f32_16x16x32_bf16 v[26:29], v[212:215], v[180:183], v[26:29]
	v_mfma_f32_16x16x32_bf16 v[18:21], v[204:207], v[188:191], v[18:21]
	v_mfma_f32_16x16x32_bf16 v[10:13], v[212:215], v[188:191], v[10:13]
	v_mfma_f32_16x16x32_bf16 v[6:9], v[204:207], v[196:199], v[6:9]
	v_mfma_f32_16x16x32_bf16 v[2:5], v[212:215], v[196:199], v[2:5]
	v_mfma_f32_16x16x32_bf16 v[50:53], v[208:211], v[176:179], v[50:53]
	v_mfma_f32_16x16x32_bf16 v[42:45], v[216:219], v[176:179], v[42:45]
	v_mfma_f32_16x16x32_bf16 v[34:37], v[208:211], v[184:187], v[34:37]
	v_mfma_f32_16x16x32_bf16 v[26:29], v[216:219], v[184:187], v[26:29]
	v_mfma_f32_16x16x32_bf16 v[18:21], v[208:211], v[192:195], v[18:21]
	v_mfma_f32_16x16x32_bf16 v[10:13], v[216:219], v[192:195], v[10:13]
	v_mfma_f32_16x16x32_bf16 v[6:9], v[208:211], v[200:203], v[6:9]
	v_mfma_f32_16x16x32_bf16 v[2:5], v[216:219], v[200:203], v[2:5]
	s_add_i32 s55, s55, 2
	s_add_u32 s53, s53, 0x100
	s_addc_u32 s54, s54, 0
	s_add_u32 s30, s30, 0x100
	s_addc_u32 s31, s31, 0
	s_cmp_gt_u32 s55, 13
	s_barrier
	s_cbranch_scc0 .LBB0_895
	v_mov_b32_e32 v156, v147
	v_mov_b32_e32 v146, v150
	s_cmp_gt_i32 s50, 11
	s_mov_b64 s[30:31], -1
	s_cbranch_scc0 .LBB0_900
	s_cmp_eq_u32 s50, 12
	s_cselect_b64 s[0:1], -1, 0
	s_and_b64 s[0:1], s[0:1], s[18:19]
	v_cmp_gt_i32_e32 vcc, 4, v146
	s_and_b64 s[0:1], s[0:1], vcc
	s_and_saveexec_b64 s[30:31], s[0:1]
	s_cbranch_execz .LBB0_899
	s_lshl_b32 s0, s24, 8
	s_add_i32 s0, s0, s43
	v_add_u32_e32 v157, s0, v156
	v_mov_b32_e32 v158, v157
	v_lshlrev_b32_e32 v148, 3, v146
	v_ashrrev_i32_e32 v149, 31, v148
	v_ashrrev_i32_e32 v159, 31, v158
	v_lshlrev_b64 v[158:159], 7, v[158:159]
	v_lshl_add_u64 v[158:159], s[14:15], 0, v[158:159]
	v_lshlrev_b64 v[148:149], 2, v[148:149]
	v_lshl_add_u64 v[162:163], v[158:159], 0, v[148:149]
	v_pk_add_f32 v[160:161], v[128:129], 0 op_sel_hi:[1,0]
	v_pk_add_f32 v[158:159], v[126:127], 0 op_sel_hi:[1,0]
	global_store_dwordx4 v[162:163], v[158:161], off
	s_nop 1
	v_pk_add_f32 v[160:161], v[124:125], 0 op_sel_hi:[1,0]
	v_pk_add_f32 v[158:159], v[122:123], 0 op_sel_hi:[1,0]
	global_store_dwordx4 v[162:163], v[158:161], off offset:16
	s_nop 1
	v_add_u32_e32 v158, 16, v157
	v_pk_add_f32 v[160:161], v[120:121], 0 op_sel_hi:[1,0]
	v_ashrrev_i32_e32 v159, 31, v158
	v_lshlrev_b64 v[158:159], 7, v[158:159]
	v_lshl_add_u64 v[158:159], s[14:15], 0, v[158:159]
	v_lshl_add_u64 v[162:163], v[158:159], 0, v[148:149]
	v_pk_add_f32 v[158:159], v[118:119], 0 op_sel_hi:[1,0]
	global_store_dwordx4 v[162:163], v[158:161], off
	s_nop 1
	v_pk_add_f32 v[160:161], v[112:113], 0 op_sel_hi:[1,0]
	v_pk_add_f32 v[158:159], v[110:111], 0 op_sel_hi:[1,0]
	global_store_dwordx4 v[162:163], v[158:161], off offset:16
	s_nop 1
	v_add_u32_e32 v158, 32, v157
	v_pk_add_f32 v[160:161], v[104:105], 0 op_sel_hi:[1,0]
	v_ashrrev_i32_e32 v159, 31, v158
	v_lshlrev_b64 v[158:159], 7, v[158:159]
	v_lshl_add_u64 v[158:159], s[14:15], 0, v[158:159]
	v_lshl_add_u64 v[162:163], v[158:159], 0, v[148:149]
	v_pk_add_f32 v[158:159], v[102:103], 0 op_sel_hi:[1,0]
	global_store_dwordx4 v[162:163], v[158:161], off
	s_nop 1
	v_pk_add_f32 v[160:161], v[96:97], 0 op_sel_hi:[1,0]
	v_pk_add_f32 v[158:159], v[94:95], 0 op_sel_hi:[1,0]
	global_store_dwordx4 v[162:163], v[158:161], off offset:16
	s_nop 1
	v_add_u32_e32 v158, 48, v157
	v_pk_add_f32 v[160:161], v[88:89], 0 op_sel_hi:[1,0]
	v_ashrrev_i32_e32 v159, 31, v158
	v_lshlrev_b64 v[158:159], 7, v[158:159]
	v_lshl_add_u64 v[158:159], s[14:15], 0, v[158:159]
	v_lshl_add_u64 v[162:163], v[158:159], 0, v[148:149]
	v_pk_add_f32 v[158:159], v[86:87], 0 op_sel_hi:[1,0]
	global_store_dwordx4 v[162:163], v[158:161], off
	s_nop 1
	v_pk_add_f32 v[160:161], v[80:81], 0 op_sel_hi:[1,0]
	v_pk_add_f32 v[158:159], v[78:79], 0 op_sel_hi:[1,0]
	global_store_dwordx4 v[162:163], v[158:161], off offset:16
	s_nop 1
	v_add_u32_e32 v158, 0x80, v157
	v_pk_add_f32 v[160:161], v[64:65], 0 op_sel_hi:[1,0]
	v_ashrrev_i32_e32 v159, 31, v158
	v_lshlrev_b64 v[158:159], 7, v[158:159]
	v_lshl_add_u64 v[158:159], s[14:15], 0, v[158:159]
	v_lshl_add_u64 v[162:163], v[158:159], 0, v[148:149]
	v_pk_add_f32 v[158:159], v[62:63], 0 op_sel_hi:[1,0]
	global_store_dwordx4 v[162:163], v[158:161], off
	s_nop 1
	v_pk_add_f32 v[160:161], v[60:61], 0 op_sel_hi:[1,0]
	v_pk_add_f32 v[158:159], v[58:59], 0 op_sel_hi:[1,0]
	global_store_dwordx4 v[162:163], v[158:161], off offset:16
	s_nop 1
	v_add_u32_e32 v158, 0x90, v157
	v_pk_add_f32 v[160:161], v[56:57], 0 op_sel_hi:[1,0]
	v_ashrrev_i32_e32 v159, 31, v158
	v_lshlrev_b64 v[158:159], 7, v[158:159]
	v_lshl_add_u64 v[158:159], s[14:15], 0, v[158:159]
	v_lshl_add_u64 v[162:163], v[158:159], 0, v[148:149]
	v_pk_add_f32 v[158:159], v[54:55], 0 op_sel_hi:[1,0]
	global_store_dwordx4 v[162:163], v[158:161], off
	s_nop 1
	v_pk_add_f32 v[160:161], v[48:49], 0 op_sel_hi:[1,0]
	v_pk_add_f32 v[158:159], v[46:47], 0 op_sel_hi:[1,0]
	global_store_dwordx4 v[162:163], v[158:161], off offset:16
	s_nop 1
	v_add_u32_e32 v158, 0xa0, v157
	v_pk_add_f32 v[160:161], v[40:41], 0 op_sel_hi:[1,0]
	v_ashrrev_i32_e32 v159, 31, v158
	v_lshlrev_b64 v[158:159], 7, v[158:159]
	v_lshl_add_u64 v[158:159], s[14:15], 0, v[158:159]
	v_lshl_add_u64 v[162:163], v[158:159], 0, v[148:149]
	v_pk_add_f32 v[158:159], v[38:39], 0 op_sel_hi:[1,0]
	global_store_dwordx4 v[162:163], v[158:161], off
	s_nop 1
	v_pk_add_f32 v[160:161], v[32:33], 0 op_sel_hi:[1,0]
	v_pk_add_f32 v[158:159], v[30:31], 0 op_sel_hi:[1,0]
	global_store_dwordx4 v[162:163], v[158:161], off offset:16
	s_nop 1
	v_add_u32_e32 v158, 0xb0, v157
	v_pk_add_f32 v[160:161], v[24:25], 0 op_sel_hi:[1,0]
	v_ashrrev_i32_e32 v159, 31, v158
	v_lshlrev_b64 v[158:159], 7, v[158:159]
	v_lshl_add_u64 v[158:159], s[14:15], 0, v[158:159]
	v_lshl_add_u64 v[148:149], v[158:159], 0, v[148:149]
	v_pk_add_f32 v[158:159], v[22:23], 0 op_sel_hi:[1,0]
	global_store_dwordx4 v[148:149], v[158:161], off
	s_nop 1
	v_pk_add_f32 v[160:161], v[16:17], 0 op_sel_hi:[1,0]
	v_pk_add_f32 v[158:159], v[14:15], 0 op_sel_hi:[1,0]
	global_store_dwordx4 v[148:149], v[158:161], off offset:16
